# stack15 with s_sleep 6 instead of s_sleep 1 between barrier polls (less polling traffic on the counter line)
# baseline (speedup 1.0000x reference)
.LBB0_22:
	global_load_dword v2, v1, s[10:11] sc1
	s_mov_b64 s[12:13], -1
	s_waitcnt vmcnt(0) lgkmcnt(0)
	v_cmp_le_u32_e32 vcc, s0, v2
	s_cbranch_vccnz .LBB0_21
	s_cmp_lg_u32 s1, 0
	s_sleep 6
	s_cbranch_scc0 .LBB0_20
	global_load_dword v2, v1, s[10:11] sc1
	s_waitcnt vmcnt(0)
	v_cmp_gt_u32_e32 vcc, s0, v2
	s_cbranch_vccz .LBB0_21
	s_sleep 6
	global_load_dword v2, v1, s[10:11] sc1
	s_waitcnt vmcnt(0)
	v_cmp_gt_u32_e32 vcc, s0, v2
	s_cbranch_vccz .LBB0_21
	s_sleep 6
	global_load_dword v2, v1, s[10:11] sc1
	s_waitcnt vmcnt(0)
	v_cmp_gt_u32_e32 vcc, s0, v2
	s_cbranch_vccz .LBB0_21
	s_sleep 6
	global_load_dword v2, v1, s[10:11] sc1
	s_waitcnt vmcnt(0)
	v_cmp_gt_u32_e32 vcc, s0, v2
	s_cbranch_vccz .LBB0_21
	s_sleep 6
	global_load_dword v2, v1, s[10:11] sc1
	s_waitcnt vmcnt(0)
	v_cmp_gt_u32_e32 vcc, s0, v2
	s_cbranch_vccz .LBB0_21
	s_sleep 6
	global_load_dword v2, v1, s[10:11] sc1
	s_waitcnt vmcnt(0)
	v_cmp_gt_u32_e32 vcc, s0, v2
	s_cbranch_vccz .LBB0_21
	s_sleep 6
	global_load_dword v2, v1, s[10:11] sc1
	s_waitcnt vmcnt(0)
	v_cmp_gt_u32_e32 vcc, s0, v2
	s_cbranch_vccz .LBB0_21
	s_sleep 6
	s_add_i32 s1, s1, -8
	s_mov_b64 s[12:13], 0
	s_branch .LBB0_21

; DI void grid_barrier_xcd(unsigned* bar, const unsigned gen, const unsigned my_xcc, const unsigned n_local, const unsigned n_xcds) {
;     ...
;     while (__hip_atomic_load(rel, __ATOMIC_RELAXED, __HIP_MEMORY_SCOPE_AGENT) < gen) {
;       __builtin_amdgcn_s_sleep(1);
;       if (++spins > (1u << 24)) break;
;     }
.LBB0_44:
	global_load_dword v2, v1, s[10:11] sc1
	s_mov_b64 s[12:13], -1
	s_waitcnt vmcnt(0)
	v_cmp_ne_u32_e32 vcc, 0, v2
	s_cbranch_vccnz .LBB0_43
	s_cmp_lg_u32 s0, 0
	s_sleep 6
	s_cbranch_scc0 .LBB0_42
	global_load_dword v2, v1, s[10:11] sc1
	s_waitcnt vmcnt(0)
	v_cmp_eq_u32_e32 vcc, 0, v2
	s_cbranch_vccz .LBB0_43
	s_sleep 6
	global_load_dword v2, v1, s[10:11] sc1
	s_waitcnt vmcnt(0)
	v_cmp_eq_u32_e32 vcc, 0, v2
	s_cbranch_vccz .LBB0_43
	s_sleep 6
	global_load_dword v2, v1, s[10:11] sc1
	s_waitcnt vmcnt(0)
	v_cmp_eq_u32_e32 vcc, 0, v2
	s_cbranch_vccz .LBB0_43
	s_sleep 6
	global_load_dword v2, v1, s[10:11] sc1
	s_waitcnt vmcnt(0)
	v_cmp_eq_u32_e32 vcc, 0, v2
	s_cbranch_vccz .LBB0_43
	s_sleep 6
	global_load_dword v2, v1, s[10:11] sc1
	s_waitcnt vmcnt(0)
	v_cmp_eq_u32_e32 vcc, 0, v2
	s_cbranch_vccz .LBB0_43
	s_sleep 6
	global_load_dword v2, v1, s[10:11] sc1
	s_waitcnt vmcnt(0)
	v_cmp_eq_u32_e32 vcc, 0, v2
	s_cbranch_vccz .LBB0_43
	s_sleep 6
	global_load_dword v2, v1, s[10:11] sc1
	s_waitcnt vmcnt(0)
	v_cmp_eq_u32_e32 vcc, 0, v2
	s_cbranch_vccz .LBB0_43
	s_sleep 6
	s_add_i32 s0, s0, -8
	s_mov_b64 s[12:13], 0
	s_branch .LBB0_43

; DI void grid_barrier_xcd(unsigned* bar, const unsigned gen, const unsigned my_xcc, const unsigned n_local, const unsigned n_xcds) {
;     ...
;     while (__hip_atomic_load(rel, __ATOMIC_RELAXED, __HIP_MEMORY_SCOPE_AGENT) < gen) {
;       __builtin_amdgcn_s_sleep(1);
;       if (++spins > (1u << 24)) break;
;     }
.LBB0_138:
	global_load_dword v2, v1, s[10:11] sc1
	s_mov_b64 s[12:13], -1
	s_waitcnt vmcnt(0)
	v_cmp_lt_u32_e32 vcc, s101, v2
	s_cbranch_vccnz .LBB0_137
	s_cmp_lg_u32 s0, 0
	s_sleep 6
	s_cbranch_scc0 .LBB0_136
	global_load_dword v2, v1, s[10:11] sc1
	s_waitcnt vmcnt(0)
	v_cmp_ge_u32_e32 vcc, s101, v2
	s_cbranch_vccz .LBB0_137
	s_sleep 6
	global_load_dword v2, v1, s[10:11] sc1
	s_waitcnt vmcnt(0)
	v_cmp_ge_u32_e32 vcc, s101, v2
	s_cbranch_vccz .LBB0_137
	s_sleep 6
	global_load_dword v2, v1, s[10:11] sc1
	s_waitcnt vmcnt(0)
	v_cmp_ge_u32_e32 vcc, s101, v2
	s_cbranch_vccz .LBB0_137
	s_sleep 6
	global_load_dword v2, v1, s[10:11] sc1
	s_waitcnt vmcnt(0)
	v_cmp_ge_u32_e32 vcc, s101, v2
	s_cbranch_vccz .LBB0_137
	s_sleep 6
	global_load_dword v2, v1, s[10:11] sc1
	s_waitcnt vmcnt(0)
	v_cmp_ge_u32_e32 vcc, s101, v2
	s_cbranch_vccz .LBB0_137
	s_sleep 6
	global_load_dword v2, v1, s[10:11] sc1
	s_waitcnt vmcnt(0)
	v_cmp_ge_u32_e32 vcc, s101, v2
	s_cbranch_vccz .LBB0_137
	s_sleep 6
	global_load_dword v2, v1, s[10:11] sc1
	s_waitcnt vmcnt(0)
	v_cmp_ge_u32_e32 vcc, s101, v2
	s_cbranch_vccz .LBB0_137
	s_sleep 6
	s_add_i32 s0, s0, -8
	s_mov_b64 s[12:13], 0
	s_branch .LBB0_137

.LBB0_309:
	global_load_dword v2, v1, s[8:9] sc1
	s_mov_b64 s[12:13], -1
	s_waitcnt vmcnt(0) lgkmcnt(0)
	v_cmp_le_u32_e32 vcc, s0, v2
	s_cbranch_vccnz .LBB0_308
	s_cmp_lg_u32 s1, 0
	s_sleep 6
	s_cbranch_scc0 .LBB0_307
	global_load_dword v2, v1, s[8:9] sc1
	s_waitcnt vmcnt(0)
	v_cmp_gt_u32_e32 vcc, s0, v2
	s_cbranch_vccz .LBB0_308
	s_sleep 6
	global_load_dword v2, v1, s[8:9] sc1
	s_waitcnt vmcnt(0)
	v_cmp_gt_u32_e32 vcc, s0, v2
	s_cbranch_vccz .LBB0_308
	s_sleep 6
	global_load_dword v2, v1, s[8:9] sc1
	s_waitcnt vmcnt(0)
	v_cmp_gt_u32_e32 vcc, s0, v2
	s_cbranch_vccz .LBB0_308
	s_sleep 6
	global_load_dword v2, v1, s[8:9] sc1
	s_waitcnt vmcnt(0)
	v_cmp_gt_u32_e32 vcc, s0, v2
	s_cbranch_vccz .LBB0_308
	s_sleep 6
	global_load_dword v2, v1, s[8:9] sc1
	s_waitcnt vmcnt(0)
	v_cmp_gt_u32_e32 vcc, s0, v2
	s_cbranch_vccz .LBB0_308
	s_sleep 6
	global_load_dword v2, v1, s[8:9] sc1
	s_waitcnt vmcnt(0)
	v_cmp_gt_u32_e32 vcc, s0, v2
	s_cbranch_vccz .LBB0_308
	s_sleep 6
	global_load_dword v2, v1, s[8:9] sc1
	s_waitcnt vmcnt(0)
	v_cmp_gt_u32_e32 vcc, s0, v2
	s_cbranch_vccz .LBB0_308
	s_sleep 6
	s_add_i32 s1, s1, -8
	s_mov_b64 s[12:13], 0
	s_branch .LBB0_308

; DI void grid_barrier_xcd(unsigned* bar, const unsigned gen, const unsigned my_xcc, const unsigned n_local, const unsigned n_xcds) {
;     ...
;     while (__hip_atomic_load(rel, __ATOMIC_RELAXED, __HIP_MEMORY_SCOPE_AGENT) < gen) {
;       __builtin_amdgcn_s_sleep(1);
;       if (++spins > (1u << 24)) break;
;     }
.LBB0_332:
	global_load_dword v2, v1, s[8:9] sc1
	s_mov_b64 s[12:13], -1
	s_waitcnt vmcnt(0)
	v_cmp_lt_u32_e32 vcc, s101, v2
	s_cbranch_vccnz .LBB0_331
	s_cmp_lg_u32 s0, 0
	s_sleep 6
	s_cbranch_scc0 .LBB0_330
	global_load_dword v2, v1, s[8:9] sc1
	s_waitcnt vmcnt(0)
	v_cmp_ge_u32_e32 vcc, s101, v2
	s_cbranch_vccz .LBB0_331
	s_sleep 6
	global_load_dword v2, v1, s[8:9] sc1
	s_waitcnt vmcnt(0)
	v_cmp_ge_u32_e32 vcc, s101, v2
	s_cbranch_vccz .LBB0_331
	s_sleep 6
	global_load_dword v2, v1, s[8:9] sc1
	s_waitcnt vmcnt(0)
	v_cmp_ge_u32_e32 vcc, s101, v2
	s_cbranch_vccz .LBB0_331
	s_sleep 6
	global_load_dword v2, v1, s[8:9] sc1
	s_waitcnt vmcnt(0)
	v_cmp_ge_u32_e32 vcc, s101, v2
	s_cbranch_vccz .LBB0_331
	s_sleep 6
	global_load_dword v2, v1, s[8:9] sc1
	s_waitcnt vmcnt(0)
	v_cmp_ge_u32_e32 vcc, s101, v2
	s_cbranch_vccz .LBB0_331
	s_sleep 6
	global_load_dword v2, v1, s[8:9] sc1
	s_waitcnt vmcnt(0)
	v_cmp_ge_u32_e32 vcc, s101, v2
	s_cbranch_vccz .LBB0_331
	s_sleep 6
	global_load_dword v2, v1, s[8:9] sc1
	s_waitcnt vmcnt(0)
	v_cmp_ge_u32_e32 vcc, s101, v2
	s_cbranch_vccz .LBB0_331
	s_sleep 6
	s_add_i32 s0, s0, -8
	s_mov_b64 s[12:13], 0
	s_branch .LBB0_331

.LBB0_467:
	global_load_dword v3, v2, s[10:11] sc1
	s_mov_b64 s[12:13], -1
	s_waitcnt vmcnt(0)
	v_cmp_le_u32_e32 vcc, s0, v3
	s_cbranch_vccnz .LBB0_466
	s_cmp_lg_u32 s1, 0
	s_sleep 6
	s_cbranch_scc0 .LBB0_465
	global_load_dword v3, v2, s[10:11] sc1
	s_waitcnt vmcnt(0)
	v_cmp_gt_u32_e32 vcc, s0, v3
	s_cbranch_vccz .LBB0_466
	s_sleep 6
	global_load_dword v3, v2, s[10:11] sc1
	s_waitcnt vmcnt(0)
	v_cmp_gt_u32_e32 vcc, s0, v3
	s_cbranch_vccz .LBB0_466
	s_sleep 6
	global_load_dword v3, v2, s[10:11] sc1
	s_waitcnt vmcnt(0)
	v_cmp_gt_u32_e32 vcc, s0, v3
	s_cbranch_vccz .LBB0_466
	s_sleep 6
	global_load_dword v3, v2, s[10:11] sc1
	s_waitcnt vmcnt(0)
	v_cmp_gt_u32_e32 vcc, s0, v3
	s_cbranch_vccz .LBB0_466
	s_sleep 6
	global_load_dword v3, v2, s[10:11] sc1
	s_waitcnt vmcnt(0)
	v_cmp_gt_u32_e32 vcc, s0, v3
	s_cbranch_vccz .LBB0_466
	s_sleep 6
	global_load_dword v3, v2, s[10:11] sc1
	s_waitcnt vmcnt(0)
	v_cmp_gt_u32_e32 vcc, s0, v3
	s_cbranch_vccz .LBB0_466
	s_sleep 6
	global_load_dword v3, v2, s[10:11] sc1
	s_waitcnt vmcnt(0)
	v_cmp_gt_u32_e32 vcc, s0, v3
	s_cbranch_vccz .LBB0_466
	s_sleep 6
	s_add_i32 s1, s1, -8
	s_mov_b64 s[12:13], 0
	s_branch .LBB0_466

; DI void grid_barrier_xcd(unsigned* bar, const unsigned gen, const unsigned my_xcc, const unsigned n_local, const unsigned n_xcds) {
;     ...
;     while (__hip_atomic_load(rel, __ATOMIC_RELAXED, __HIP_MEMORY_SCOPE_AGENT) < gen) {
;       __builtin_amdgcn_s_sleep(1);
;       if (++spins > (1u << 24)) break;
;     }
.LBB0_490:
	global_load_dword v3, v2, s[10:11] sc1
	s_mov_b64 s[12:13], -1
	s_waitcnt vmcnt(0)
	v_cmp_lt_u32_e32 vcc, s101, v3
	s_cbranch_vccnz .LBB0_489
	s_cmp_lg_u32 s0, 0
	s_sleep 6
	s_cbranch_scc0 .LBB0_488
	global_load_dword v3, v2, s[10:11] sc1
	s_waitcnt vmcnt(0)
	v_cmp_ge_u32_e32 vcc, s101, v3
	s_cbranch_vccz .LBB0_489
	s_sleep 6
	global_load_dword v3, v2, s[10:11] sc1
	s_waitcnt vmcnt(0)
	v_cmp_ge_u32_e32 vcc, s101, v3
	s_cbranch_vccz .LBB0_489
	s_sleep 6
	global_load_dword v3, v2, s[10:11] sc1
	s_waitcnt vmcnt(0)
	v_cmp_ge_u32_e32 vcc, s101, v3
	s_cbranch_vccz .LBB0_489
	s_sleep 6
	global_load_dword v3, v2, s[10:11] sc1
	s_waitcnt vmcnt(0)
	v_cmp_ge_u32_e32 vcc, s101, v3
	s_cbranch_vccz .LBB0_489
	s_sleep 6
	global_load_dword v3, v2, s[10:11] sc1
	s_waitcnt vmcnt(0)
	v_cmp_ge_u32_e32 vcc, s101, v3
	s_cbranch_vccz .LBB0_489
	s_sleep 6
	global_load_dword v3, v2, s[10:11] sc1
	s_waitcnt vmcnt(0)
	v_cmp_ge_u32_e32 vcc, s101, v3
	s_cbranch_vccz .LBB0_489
	s_sleep 6
	global_load_dword v3, v2, s[10:11] sc1
	s_waitcnt vmcnt(0)
	v_cmp_ge_u32_e32 vcc, s101, v3
	s_cbranch_vccz .LBB0_489
	s_sleep 6
	s_add_i32 s0, s0, -8
	s_mov_b64 s[12:13], 0
	s_branch .LBB0_489

.LBB0_577:
	s_waitcnt lgkmcnt(0)
	global_load_dword v2, v1, s[10:11] sc1
	s_mov_b64 s[12:13], -1
	s_waitcnt vmcnt(0)
	v_cmp_le_u32_e32 vcc, s0, v2
	s_cbranch_vccnz .LBB0_576
	s_cmp_lg_u32 s1, 0
	s_sleep 6
	s_cbranch_scc0 .LBB0_575
	global_load_dword v2, v1, s[10:11] sc1
	s_waitcnt vmcnt(0)
	v_cmp_gt_u32_e32 vcc, s0, v2
	s_cbranch_vccz .LBB0_576
	s_sleep 6
	global_load_dword v2, v1, s[10:11] sc1
	s_waitcnt vmcnt(0)
	v_cmp_gt_u32_e32 vcc, s0, v2
	s_cbranch_vccz .LBB0_576
	s_sleep 6
	global_load_dword v2, v1, s[10:11] sc1
	s_waitcnt vmcnt(0)
	v_cmp_gt_u32_e32 vcc, s0, v2
	s_cbranch_vccz .LBB0_576
	s_sleep 6
	global_load_dword v2, v1, s[10:11] sc1
	s_waitcnt vmcnt(0)
	v_cmp_gt_u32_e32 vcc, s0, v2
	s_cbranch_vccz .LBB0_576
	s_sleep 6
	global_load_dword v2, v1, s[10:11] sc1
	s_waitcnt vmcnt(0)
	v_cmp_gt_u32_e32 vcc, s0, v2
	s_cbranch_vccz .LBB0_576
	s_sleep 6
	global_load_dword v2, v1, s[10:11] sc1
	s_waitcnt vmcnt(0)
	v_cmp_gt_u32_e32 vcc, s0, v2
	s_cbranch_vccz .LBB0_576
	s_sleep 6
	global_load_dword v2, v1, s[10:11] sc1
	s_waitcnt vmcnt(0)
	v_cmp_gt_u32_e32 vcc, s0, v2
	s_cbranch_vccz .LBB0_576
	s_sleep 6
	s_add_i32 s1, s1, -8
	s_mov_b64 s[12:13], 0
	s_branch .LBB0_576

; DI void grid_barrier_xcd(unsigned* bar, const unsigned gen, const unsigned my_xcc, const unsigned n_local, const unsigned n_xcds) {
;     ...
;     while (__hip_atomic_load(rel, __ATOMIC_RELAXED, __HIP_MEMORY_SCOPE_AGENT) < gen) {
;       __builtin_amdgcn_s_sleep(1);
;       if (++spins > (1u << 24)) break;
;     }
.LBB0_599:
	global_load_dword v2, v1, s[4:5] sc1
	s_mov_b64 s[10:11], -1
	s_waitcnt vmcnt(0)
	v_cmp_lt_u32_e32 vcc, s101, v2
	s_cbranch_vccnz .LBB0_598
	s_cmp_lg_u32 s0, 0
	s_sleep 6
	s_cbranch_scc0 .LBB0_597
	global_load_dword v2, v1, s[4:5] sc1
	s_waitcnt vmcnt(0)
	v_cmp_ge_u32_e32 vcc, s101, v2
	s_cbranch_vccz .LBB0_598
	s_sleep 6
	global_load_dword v2, v1, s[4:5] sc1
	s_waitcnt vmcnt(0)
	v_cmp_ge_u32_e32 vcc, s101, v2
	s_cbranch_vccz .LBB0_598
	s_sleep 6
	global_load_dword v2, v1, s[4:5] sc1
	s_waitcnt vmcnt(0)
	v_cmp_ge_u32_e32 vcc, s101, v2
	s_cbranch_vccz .LBB0_598
	s_sleep 6
	global_load_dword v2, v1, s[4:5] sc1
	s_waitcnt vmcnt(0)
	v_cmp_ge_u32_e32 vcc, s101, v2
	s_cbranch_vccz .LBB0_598
	s_sleep 6
	global_load_dword v2, v1, s[4:5] sc1
	s_waitcnt vmcnt(0)
	v_cmp_ge_u32_e32 vcc, s101, v2
	s_cbranch_vccz .LBB0_598
	s_sleep 6
	global_load_dword v2, v1, s[4:5] sc1
	s_waitcnt vmcnt(0)
	v_cmp_ge_u32_e32 vcc, s101, v2
	s_cbranch_vccz .LBB0_598
	s_sleep 6
	global_load_dword v2, v1, s[4:5] sc1
	s_waitcnt vmcnt(0)
	v_cmp_ge_u32_e32 vcc, s101, v2
	s_cbranch_vccz .LBB0_598
	s_sleep 6
	s_add_i32 s0, s0, -8
	s_mov_b64 s[10:11], 0
	s_branch .LBB0_598
